# XCD-local grid barrier after P6 and P8 (row-tile ownership is XCD-local there): leader skips L2 writeback + cross-XCD stage; workgroup order id derived from (XCC id, census rank) so ownership group ==
# speedup vs baseline: 1.0220x; 1.0017x over previous
; #define LAS __attribute__((address_space(3)))
; __device__ __forceinline__ unsigned xb_add(unsigned* p, unsigned v) { return __hip_atomic_fetch_add(p, v, __ATOMIC_RELAXED, __HIP_MEMORY_SCOPE_AGENT); }
; __device__ __forceinline__ unsigned xb_xcc_id() { return (unsigned)__builtin_amdgcn_s_getreg((3 << 11) | 20) & 0xFu; }
; #define ws OPQ_PTR(unsigned char*, ws)
; __device__ __forceinline__ XcdBarrier xcd_barrier_post(unsigned* bar, volatile LAS unsigned* st) {
;     XcdBarrier b; b.bar = bar; b.x = xb_xcc_id(); b.st = st;
;     if (threadIdx.x == 0) (void)xb_add(&bar[XB_XCNT(b.x)], 1u);
;     return b;
; }
; __global__ void __launch_bounds__(NTHR, 2) fwd_kernel(Args A) {
;     ...
;     if (threadIdx.x < 32) ((LAS unsigned*)(lds + MISC_OFF))[threadIdx.x] = (threadIdx.x == 16) ? (unsigned)blockIdx.x : 0u;
;     __syncthreads();
;     (void)xcd_barrier_post((unsigned*)(A.ws + WS_CTL), (volatile LAS unsigned*)(lds + MISC_OFF) + 8);
.LBB0_2:
	s_or_b64 exec, exec, s[4:5]
	s_load_dwordx2 s[26:27], s[0:1], 0xb8
	s_waitcnt lgkmcnt(0)
	s_barrier
	s_getreg_b32 s6, hwreg(HW_REG_XCC_ID, 0, 4)
	v_cmp_eq_u32_e64 s[4:5], 0, v1
	s_mov_b64 s[2:3], exec
	s_nop 0
	v_writelane_b32 v255, s4, 0
	s_nop 1
	v_writelane_b32 v255, s5, 1
	s_and_b64 s[4:5], s[2:3], s[4:5]
	s_mov_b64 exec, s[4:5]
	s_cbranch_execz .LBB0_5
	s_mov_b64 s[4:5], exec
	v_mbcnt_lo_u32_b32 v2, s4, 0
	v_mbcnt_hi_u32_b32 v2, s5, v2
	v_cmp_eq_u32_e32 vcc, 0, v2
	s_and_b64 s[8:9], exec, vcc
	s_mov_b64 exec, s[8:9]
	s_cbranch_execz .LBB0_5
	s_and_b32 s9, s6, 7
	s_lshl_b32 s6, s6, 8
	s_and_b32 s6, s6, 0xf00
	s_add_u32 s6, s26, s6
	s_addc_u32 s7, s27, 0
	s_bcnt1_i32_b64 s4, s[4:5]
	v_mov_b32_e32 v2, 0x34800000
	v_mov_b32_e32 v3, s4
	global_atomic_add v3, v2, v3, s[6:7] offset:1024 sc0
	s_waitcnt vmcnt(0)
	v_lshl_or_b32 v3, v3, 3, s9
	v_mov_b32_e32 v2, 0x20180
	ds_write_b32 v2, v3
	s_waitcnt lgkmcnt(0)
.LBB0_5:
	s_or_b64 exec, exec, s[2:3]
	s_barrier
	s_and_b32 s2, s38, 7
	s_cmp_eq_u32 s2, 0
	s_cselect_b64 s[4:5], -1, 0
	v_writelane_b32 v255, s4, 2
	v_mov_b32 v2, 0x20180
	ds_read_b32 v2, v2
	s_waitcnt lgkmcnt(0)
	s_cmp_lg_u32 s2, 0
	v_readfirstlane_b32 s43, v2
	v_writelane_b32 v255, s5, 3
	s_cbranch_scc1 .LBB0_7
	s_ashr_i32 s2, s43, 31
	s_lshr_b32 s2, s2, 29
	s_add_i32 s2, s43, s2
	s_ashr_i32 s3, s2, 3
	s_and_b32 s2, s2, -8
	s_sub_i32 s2, s43, s2
	s_ashr_i32 s4, s38, 3
	s_mul_i32 s2, s2, s4
	s_add_i32 s43, s2, s3

; __device__ __forceinline__ unsigned xb_ld(unsigned* p)              { return __hip_atomic_load(p, __ATOMIC_RELAXED, __HIP_MEMORY_SCOPE_AGENT); }
; __device__ __forceinline__ unsigned xb_add(unsigned* p, unsigned v) { return __hip_atomic_fetch_add(p, v, __ATOMIC_RELAXED, __HIP_MEMORY_SCOPE_AGENT); }
; #define XB_SPIN(cond, bar) do { unsigned _sp = 0; while (cond) { __builtin_amdgcn_s_sleep(1); \
;     if ((++_sp & 255u) == 0u) { if (xb_ld(&(bar)[XB_TMO])) break; if (_sp > XB_SPIN_CAP) { atomicAdd(&(bar)[XB_TMO], 1u); break; } } } } while (0)
; __device__ __forceinline__ void xcd_barrier(const XcdBarrier& b) {
;     asm volatile("s_waitcnt vmcnt(0)" ::: "memory");
;     __syncthreads();
;     if (threadIdx.x == 0) {
;         unsigned* bar = b.bar;
;         __builtin_amdgcn_s_waitcnt(0);
;         unsigned nloc = b.st[0], nx = b.st[1];
;         if (nloc == 0u) { xcd_barrier_complete(bar, b.x, nloc, nx); b.st[0] = nloc; b.st[1] = nx; }
;         const unsigned old = xb_add(&bar[XB_XSUB(b.x)], 1u);
;         const unsigned gen = old / nloc;
;         if (old + 1u == (gen + 1u) * nloc) {
;             __builtin_amdgcn_fence(__ATOMIC_RELEASE, "agent");
;             asm volatile("s_waitcnt vmcnt(0)" ::: "memory");
;             const unsigned og = xb_add(&bar[XB_TOP], 1u);
;             const unsigned tg = og / nx;
;             if (og + 1u == (tg + 1u) * nx) xb_add(&bar[XB_TOPGEN], 1u);
;             else XB_SPIN(xb_ld(&bar[XB_TOPGEN]) == tg, bar);
;             __builtin_amdgcn_fence(__ATOMIC_ACQUIRE, "agent");
;             xb_add(&bar[XB_XGEN(b.x)], 1u);
;             asm volatile("s_waitcnt vmcnt(0)" ::: "memory");
;         } else {
;             XB_SPIN(xb_ld(&bar[XB_XGEN(b.x)]) == gen, bar);
;             __builtin_amdgcn_fence(__ATOMIC_ACQUIRE, "agent");
;             asm volatile("s_waitcnt vmcnt(0)" ::: "memory");
;         }
;     }
;     __syncthreads();
; }
.LBB0_1135:
	s_andn2_saveexec_b64 s[6:7], s[4:5]
	s_cbranch_execz .LBB0_1151
	v_mov_b32_e32 v0, s25
	v_add_co_u32_e32 v2, vcc, 0x2000, v0
	v_mov_b32_e32 v0, s24
	s_nop 0
	v_addc_co_u32_e32 v3, vcc, 0, v0, vcc
	v_mov_b32_e32 v0, 1
	s_waitcnt vmcnt(0) lgkmcnt(0)
	buffer_inv sc1
	flat_atomic_add v[2:3], v0 offset:1024
	s_waitcnt vmcnt(0)

; __device__ __forceinline__ unsigned xb_ld(unsigned* p)              { return __hip_atomic_load(p, __ATOMIC_RELAXED, __HIP_MEMORY_SCOPE_AGENT); }
; __device__ __forceinline__ unsigned xb_add(unsigned* p, unsigned v) { return __hip_atomic_fetch_add(p, v, __ATOMIC_RELAXED, __HIP_MEMORY_SCOPE_AGENT); }
; #define XB_SPIN(cond, bar) do { unsigned _sp = 0; while (cond) { __builtin_amdgcn_s_sleep(1); \
;     if ((++_sp & 255u) == 0u) { if (xb_ld(&(bar)[XB_TMO])) break; if (_sp > XB_SPIN_CAP) { atomicAdd(&(bar)[XB_TMO], 1u); break; } } } } while (0)
; __device__ __forceinline__ void xcd_barrier(const XcdBarrier& b) {
;     asm volatile("s_waitcnt vmcnt(0)" ::: "memory");
;     __syncthreads();
;     if (threadIdx.x == 0) {
;         unsigned* bar = b.bar;
;         __builtin_amdgcn_s_waitcnt(0);
;         unsigned nloc = b.st[0], nx = b.st[1];
;         if (nloc == 0u) { xcd_barrier_complete(bar, b.x, nloc, nx); b.st[0] = nloc; b.st[1] = nx; }
;         const unsigned old = xb_add(&bar[XB_XSUB(b.x)], 1u);
;         const unsigned gen = old / nloc;
;         if (old + 1u == (gen + 1u) * nloc) {
;             __builtin_amdgcn_fence(__ATOMIC_RELEASE, "agent");
;             asm volatile("s_waitcnt vmcnt(0)" ::: "memory");
;             const unsigned og = xb_add(&bar[XB_TOP], 1u);
;             const unsigned tg = og / nx;
;             if (og + 1u == (tg + 1u) * nx) xb_add(&bar[XB_TOPGEN], 1u);
;             else XB_SPIN(xb_ld(&bar[XB_TOPGEN]) == tg, bar);
;             __builtin_amdgcn_fence(__ATOMIC_ACQUIRE, "agent");
;             xb_add(&bar[XB_XGEN(b.x)], 1u);
;             asm volatile("s_waitcnt vmcnt(0)" ::: "memory");
;         } else {
;             XB_SPIN(xb_ld(&bar[XB_XGEN(b.x)]) == gen, bar);
;             __builtin_amdgcn_fence(__ATOMIC_ACQUIRE, "agent");
;             asm volatile("s_waitcnt vmcnt(0)" ::: "memory");
;         }
;     }
;     __syncthreads();
; }
.LBB0_1206:
	s_andn2_saveexec_b64 s[2:3], s[4:5]
	s_cbranch_execz .LBB0_1222
	v_mov_b32_e32 v0, s25
	v_add_co_u32_e32 v2, vcc, 0x2000, v0
	v_mov_b32_e32 v0, s24
	s_nop 0
	v_addc_co_u32_e32 v3, vcc, 0, v0, vcc
	v_mov_b32_e32 v0, 1
	s_waitcnt vmcnt(0) lgkmcnt(0)
	buffer_inv sc1
	flat_atomic_add v[2:3], v0 offset:1024
	s_waitcnt vmcnt(0)
